# diff-attn softmax: latent Q pre-scaled by 0.125*log2e in f32 before its bf16 rounding (w_in epilogue), -m folded into QK accumulator init, 32 v_fma per tile removed
# speedup vs baseline: 1.0144x; 1.0114x over previous
; DI void gemm_phase(const GemmArgs& g, char* shm_c) {
;     ...
;     if (g.mode == 0) {
; #pragma unroll
;       for (int ai = 0; ai < 2; ++ai)
; #pragma unroll
;         for (int m = 0; m < 4; ++m) {
;           const int row = brow + ai * HALF + wr * 64 + m * 16 + fr;
;           bf16_t* rp0 = g.Ob + (size_t)row * g.N + bcol + wc * 32;
; #pragma unroll
;           for (int bj = 0; bj < 2; ++bj) {
;             f32x4 v0 = acc[ai][bj][m][0], v1 = acc[ai][bj][m][1];
;             const int gb = bcol + bj * HALF + wc * 32;
;             if (g.rope != nullptr && gb >= 512 && gb < 1536 && brow < TL) {
;               const int sq = row & (SEQ - 1), pos = (gb & 32) ? (sq & 63) : (sq >> 6);
;               const float* rt = g.rope + (pos * 16 + 4 * fq) * 2;
;               const f32x4 t0 = *(const f32x4*)rt, t1 = *(const f32x4*)(rt + 4);
;               const f32x4 cs = {t0[0], t0[2], t1[0], t1[2]}, sn = {t0[1], t0[3], t1[1], t1[3]};
;               const f32x4 r0 = v0 * cs - v1 * sn, r1 = v1 * cs + v0 * sn;
;               v0 = r0; v1 = r1;
.LBB0_237:
	s_lshl_b32 s1, s0, 8
	s_add_i32 s1, s1, 0xfffffe00
	s_cmpk_lt_u32 s1, 0x200
	s_cselect_b32 s1, 1, 0
	s_cmp_lt_i32 s6, 64
	s_cselect_b32 s2, 1, 0
	s_and_b32 s1, s1, s2
	s_cmp_eq_u32 s1, 0
	s_cbranch_scc1 .Lwin_noqscale
	v_mov_b32_e32 v196, 0x3e38aa3b
	s_nop 7
	v_pk_mul_f32 v[2:3], v[2:3], v[196:197] op_sel_hi:[1,0]
	v_pk_mul_f32 v[4:5], v[4:5], v[196:197] op_sel_hi:[1,0]
	v_pk_mul_f32 v[6:7], v[6:7], v[196:197] op_sel_hi:[1,0]
	v_pk_mul_f32 v[8:9], v[8:9], v[196:197] op_sel_hi:[1,0]
	v_pk_mul_f32 v[10:11], v[10:11], v[196:197] op_sel_hi:[1,0]
	v_pk_mul_f32 v[12:13], v[12:13], v[196:197] op_sel_hi:[1,0]
	v_pk_mul_f32 v[14:15], v[14:15], v[196:197] op_sel_hi:[1,0]
	v_pk_mul_f32 v[16:17], v[16:17], v[196:197] op_sel_hi:[1,0]
	v_pk_mul_f32 v[18:19], v[18:19], v[196:197] op_sel_hi:[1,0]
	v_pk_mul_f32 v[20:21], v[20:21], v[196:197] op_sel_hi:[1,0]
	v_pk_mul_f32 v[22:23], v[22:23], v[196:197] op_sel_hi:[1,0]
	v_pk_mul_f32 v[24:25], v[24:25], v[196:197] op_sel_hi:[1,0]
	v_pk_mul_f32 v[26:27], v[26:27], v[196:197] op_sel_hi:[1,0]
	v_pk_mul_f32 v[28:29], v[28:29], v[196:197] op_sel_hi:[1,0]
	v_pk_mul_f32 v[30:31], v[30:31], v[196:197] op_sel_hi:[1,0]
	v_pk_mul_f32 v[32:33], v[32:33], v[196:197] op_sel_hi:[1,0]
	v_pk_mul_f32 v[34:35], v[34:35], v[196:197] op_sel_hi:[1,0]
	v_pk_mul_f32 v[36:37], v[36:37], v[196:197] op_sel_hi:[1,0]
	v_pk_mul_f32 v[38:39], v[38:39], v[196:197] op_sel_hi:[1,0]
	v_pk_mul_f32 v[40:41], v[40:41], v[196:197] op_sel_hi:[1,0]
	v_pk_mul_f32 v[42:43], v[42:43], v[196:197] op_sel_hi:[1,0]
	v_pk_mul_f32 v[44:45], v[44:45], v[196:197] op_sel_hi:[1,0]
	v_pk_mul_f32 v[46:47], v[46:47], v[196:197] op_sel_hi:[1,0]
	v_pk_mul_f32 v[48:49], v[48:49], v[196:197] op_sel_hi:[1,0]
	v_pk_mul_f32 v[50:51], v[50:51], v[196:197] op_sel_hi:[1,0]
	v_pk_mul_f32 v[52:53], v[52:53], v[196:197] op_sel_hi:[1,0]
	v_pk_mul_f32 v[54:55], v[54:55], v[196:197] op_sel_hi:[1,0]
	v_pk_mul_f32 v[56:57], v[56:57], v[196:197] op_sel_hi:[1,0]
	v_pk_mul_f32 v[58:59], v[58:59], v[196:197] op_sel_hi:[1,0]
	v_pk_mul_f32 v[60:61], v[60:61], v[196:197] op_sel_hi:[1,0]
	v_pk_mul_f32 v[62:63], v[62:63], v[196:197] op_sel_hi:[1,0]
	v_pk_mul_f32 v[64:65], v[64:65], v[196:197] op_sel_hi:[1,0]
	v_pk_mul_f32 v[66:67], v[66:67], v[196:197] op_sel_hi:[1,0]
	v_pk_mul_f32 v[68:69], v[68:69], v[196:197] op_sel_hi:[1,0]
	v_pk_mul_f32 v[70:71], v[70:71], v[196:197] op_sel_hi:[1,0]
	v_pk_mul_f32 v[72:73], v[72:73], v[196:197] op_sel_hi:[1,0]
	v_pk_mul_f32 v[74:75], v[74:75], v[196:197] op_sel_hi:[1,0]
	v_pk_mul_f32 v[76:77], v[76:77], v[196:197] op_sel_hi:[1,0]
	v_pk_mul_f32 v[78:79], v[78:79], v[196:197] op_sel_hi:[1,0]
	v_pk_mul_f32 v[80:81], v[80:81], v[196:197] op_sel_hi:[1,0]
	v_pk_mul_f32 v[82:83], v[82:83], v[196:197] op_sel_hi:[1,0]
	v_pk_mul_f32 v[84:85], v[84:85], v[196:197] op_sel_hi:[1,0]
	v_pk_mul_f32 v[86:87], v[86:87], v[196:197] op_sel_hi:[1,0]
	v_pk_mul_f32 v[88:89], v[88:89], v[196:197] op_sel_hi:[1,0]
	v_pk_mul_f32 v[90:91], v[90:91], v[196:197] op_sel_hi:[1,0]
	v_pk_mul_f32 v[92:93], v[92:93], v[196:197] op_sel_hi:[1,0]
	v_pk_mul_f32 v[94:95], v[94:95], v[196:197] op_sel_hi:[1,0]
	v_pk_mul_f32 v[96:97], v[96:97], v[196:197] op_sel_hi:[1,0]
	v_pk_mul_f32 v[98:99], v[98:99], v[196:197] op_sel_hi:[1,0]
	v_pk_mul_f32 v[100:101], v[100:101], v[196:197] op_sel_hi:[1,0]
	v_pk_mul_f32 v[102:103], v[102:103], v[196:197] op_sel_hi:[1,0]
	v_pk_mul_f32 v[104:105], v[104:105], v[196:197] op_sel_hi:[1,0]
	v_pk_mul_f32 v[106:107], v[106:107], v[196:197] op_sel_hi:[1,0]
	v_pk_mul_f32 v[108:109], v[108:109], v[196:197] op_sel_hi:[1,0]
	v_pk_mul_f32 v[110:111], v[110:111], v[196:197] op_sel_hi:[1,0]
	v_pk_mul_f32 v[112:113], v[112:113], v[196:197] op_sel_hi:[1,0]
	v_pk_mul_f32 v[114:115], v[114:115], v[196:197] op_sel_hi:[1,0]
	v_pk_mul_f32 v[116:117], v[116:117], v[196:197] op_sel_hi:[1,0]
	v_pk_mul_f32 v[118:119], v[118:119], v[196:197] op_sel_hi:[1,0]
	v_pk_mul_f32 v[120:121], v[120:121], v[196:197] op_sel_hi:[1,0]
	v_pk_mul_f32 v[122:123], v[122:123], v[196:197] op_sel_hi:[1,0]
	v_pk_mul_f32 v[124:125], v[124:125], v[196:197] op_sel_hi:[1,0]
	v_pk_mul_f32 v[126:127], v[126:127], v[196:197] op_sel_hi:[1,0]
	v_pk_mul_f32 v[128:129], v[128:129], v[196:197] op_sel_hi:[1,0]

; DI int tid_() { int t = threadIdx.x; asm volatile("" : "+v"(t)); return t; }
; DI void diff_unit(KP p, int l, int b, int h, int qb, int isctx, float lamv, float lam_init, char* ldsc) {
;   const int tid = tid_(), lane = tid & 63, w = __builtin_amdgcn_readfirstlane(tid >> 6), r = lane & 31, hh = lane >> 5;
;   const int pr = (r & ~12) | ((r & 4) << 1) | ((r & 8) >> 1);
;   const int comp = w & 1, grp = w >> 1;
;   const int qrow = (isctx ? TL + b * CTXL : b * SEQ) + qb * 128 + grp * 32 + r;
;   const int nt = isctx ? 4 : 132;
;   lds_u8* L = (lds_u8*)ldsc;
;   constexpr int STG = 32768;
;   int ko[4], vo[4];
; #pragma unroll
;   for (int ks = 0; ks < 4; ++ks) ko[ks] = pr * 128 + (((2 * ks + hh) ^ ((pr >> 1) & 7)) << 4);
; #pragma unroll
;   for (int q = 0; q < 4; ++q) vo[q] = r * 128 + (((2 * q + hh) ^ ((r >> 1) & 7)) << 4);
;   bf16x8 qf[4];
; #pragma unroll
;   for (int ks = 0; ks < 4; ++ks) qf[ks] = *(const bf16x8*)(p->P + (size_t)qrow * INC + 512 + h * 128 + comp * 64 + 16 * ks + 8 * hh);
;   f32x16 o[4];
; #pragma unroll
;   for (int d = 0; d < 4; ++d)
; #pragma unroll
;     for (int i = 0; i < 16; ++i) o[d][i] = 0.f;
;   float m, lsum;
;   const bf16_t* vt = p->Vtd + (size_t)((b * 4 + h) * 128) * NKEY;
;   const bf16_t* Pk = p->P + 1024 + h * 128;
;   const int row8 = 8 * w + (lane >> 3), swz = ((lane & 7) ^ ((row8 >> 1) & 7)) << 4;
;   const unsigned kq = (unsigned)(row8 * (INC * 2) + swz), vq = (unsigned)(row8 * (NKEY * 2) + swz);
;     ...
;   asm volatile("s_waitcnt vmcnt(0)" ::: "memory");
;   __syncthreads();
;   DISSUE(0, 0);
;   DISSUE(1, 1);
;   asm volatile("s_waitcnt vmcnt(4)" ::: "memory");
;   __builtin_amdgcn_s_barrier();
;   bf16x8 P[4];
;   {
;     f32x16 st[2];
;     qk_tile(qf, L + comp * 8192, ko, st);
;     m = tile_max(st);
;     lsum = exp_pack(st, m, P);
;   }
;   int stg = 0;
;   bool need = false; float alpha = 1.f;
;   if (w >= 4) __builtin_amdgcn_s_setprio(1);
.LBB0_468:
	s_lshl_b32 s1, s12, 5
	s_and_b32 s0, s12, 0xffffff00
	s_and_b32 s1, s1, 0xe0
	s_or_b32 s0, s1, s0
	s_bfe_u32 s1, s12, 0x50003
	v_mov_b32_e32 v38, v158
	s_or_b32 s2, s0, s1
	s_and_b64 s[0:1], s[6:7], exec
	v_lshlrev_b32_e32 v2, 1, v38
	v_lshrrev_b32_e32 v34, 1, v38
	v_and_b32_e32 v0, 19, v38
	v_and_b32_e32 v2, 8, v2
	v_and_b32_e32 v3, 4, v34
	s_load_dwordx2 s[10:11], s[80:81], 0xf8
	s_cselect_b32 s2, s2, s12
	v_or3_b32 v0, v2, v0, v3
	s_ashr_i32 s13, s2, 8
	v_readfirstlane_b32 s1, v38
	v_bfe_u32 v144, v38, 5, 1
	s_lshl_b32 s4, s2, 7
	v_lshrrev_b32_e32 v23, 1, v0
	s_ashr_i32 s15, s1, 6
	v_and_b32_e32 v35, 31, v38
	s_lshl_b32 s16, s13, 13
	s_and_b32 s4, s4, 0x1f80
	v_lshlrev_b32_e32 v22, 7, v0
	v_bitop3_b32 v0, v23, v144, 7 bitop3:0x6c
	s_ashr_i32 s1, s1, 7
	s_and_b32 s14, s2, 0xffffff00
	s_or_b32 s4, s16, s4
	v_lshl_or_b32 v141, v0, 4, v22
	v_lshl_or_b32 v0, s1, 5, v35
	s_lshl_b32 s2, s2, 1
	v_add_u32_e32 v134, s4, v0
	s_load_dwordx2 s[4:5], s[80:81], 0x108
	s_waitcnt lgkmcnt(0)
	v_mov_b64_e32 v[2:3], s[10:11]
	s_and_b32 s17, s2, 0x180
	s_and_b32 s0, s15, 1
	v_mad_i64_i32 v[2:3], s[18:19], v134, s45, v[2:3]
	s_lshl_b32 s42, s17, 1
	v_lshl_add_u64 v[2:3], v[2:3], 0, s[42:43]
	s_lshl_b32 s18, s0, 7
	s_mov_b32 s19, s43
	v_lshl_add_u64 v[2:3], v[2:3], 0, s[18:19]
	v_lshlrev_b32_e32 v132, 4, v144
	v_mov_b32_e32 v133, v1
	v_lshl_add_u64 v[2:3], v[2:3], 0, v[132:133]
	global_load_dwordx4 v[98:101], v[2:3], off offset:1024
	global_load_dwordx4 v[102:105], v[2:3], off offset:1056
	global_load_dwordx4 v[106:109], v[2:3], off offset:1088
	global_load_dwordx4 v[110:113], v[2:3], off offset:1120
	s_lshl_b32 s18, s13, 9
	s_or_b32 s2, s17, s18
	s_add_i32 s3, s14, 0x4000
	s_mul_hi_i32 s13, s2, 0x4200
	s_mulk_i32 s2, 0x4200
	v_bfe_u32 v36, v38, 3, 3
	s_add_u32 s20, s4, s2
	v_lshl_or_b32 v2, s15, 3, v36
	s_addc_u32 s21, s5, s13
	v_lshrrev_b32_e32 v0, 1, v2
	s_mul_i32 s24, s14, 0x1600
	s_add_u32 s10, s10, s42
	v_xor_b32_e32 v0, v0, v38
	s_addc_u32 s11, s11, 0
	v_lshlrev_b32_e32 v0, 4, v0
	s_add_i32 s13, s24, 0x5800000
	v_and_b32_e32 v37, 0x70, v0
	v_mul_lo_u32 v0, v2, s45
	s_mul_hi_i32 s2, s3, 0x1600
	s_add_u32 s22, s10, s13
	v_or_b32_e32 v0, v37, v0
	s_addc_u32 s23, s11, s2
	s_lshl_b32 s2, s15, 10
	v_lshl_add_u64 v[4:5], s[22:23], 0, v[0:1]
	s_add_i32 s13, s2, 0
	v_lshl_add_u64 v[6:7], v[4:5], 0, s[96:97]
	s_mov_b32 m0, s13
	v_mul_lo_u32 v2, v2, s65
	s_waitcnt vmcnt(0)
	s_barrier
	global_load_lds_dwordx4 v[6:7], off
	v_lshl_add_u64 v[4:5], v[4:5], 0, s[52:53]
	s_add_i32 m0, s13, 0x2000
	v_or_b32_e32 v2, v37, v2
	v_mov_b32_e32 v3, v1
	global_load_lds_dwordx4 v[4:5], off
	s_add_i32 m0, s13, 0x4000
	v_lshl_add_u64 v[8:9], s[20:21], 0, v[2:3]
	global_load_lds_dwordx4 v2, s[20:21]
	s_mov_b64 s[20:21], 0x108000
	s_add_i32 m0, s13, 0x6000
	s_addk_i32 s14, 0x4040
	s_add_i32 s24, s24, 0x5858000
	v_lshl_add_u64 v[2:3], v[8:9], 0, s[20:21]
	s_mul_hi_i32 s2, s14, 0x1600
	s_add_u32 s20, s10, s24
	s_addc_u32 s21, s11, s2
	global_load_lds_dwordx4 v[2:3], off
	v_lshl_add_u64 v[2:3], s[20:21], 0, v[0:1]
	v_lshl_add_u64 v[4:5], v[2:3], 0, s[96:97]
	s_add_i32 m0, s13, 0x8000
	v_lshl_add_u64 v[2:3], v[2:3], 0, s[52:53]
	global_load_lds_dwordx4 v[4:5], off
	s_add_i32 m0, s13, 0xa000
	v_lshl_add_u64 v[6:7], v[8:9], 0, s[46:47]
	global_load_lds_dwordx4 v[2:3], off
	s_add_i32 m0, s13, 0xc000
	s_mov_b64 s[20:21], 0x108080
	s_lshl_b32 s14, s0, 13
	global_load_lds_dwordx4 v[6:7], off
	v_lshl_add_u64 v[2:3], v[8:9], 0, s[20:21]
	s_add_i32 m0, s13, 0xe000
	s_add_i32 s2, s14, 0
	global_load_lds_dwordx4 v[2:3], off
	s_mov_b64 s[20:21], 0x58000
	s_add_i32 m0, s13, 0x10000
	v_lshl_add_u64 v[4:5], v[4:5], 0, s[20:21]
	v_lshl_add_u64 v[6:7], v[4:5], 0, s[46:47]
	global_load_lds_dwordx4 v[4:5], off
	s_add_i32 m0, s13, 0x12000
	s_mov_b64 s[20:21], 0x100
	global_load_lds_dwordx4 v[6:7], off
	v_lshl_add_u64 v[4:5], v[8:9], 0, s[20:21]
	s_add_i32 m0, s13, 0x14000
	s_mov_b64 s[20:21], 0x108100
	global_load_lds_dwordx4 v[4:5], off
	v_lshl_add_u64 v[6:7], v[8:9], 0, s[20:21]
	s_add_i32 m0, s13, 0x16000
	s_nop 0
	global_load_lds_dwordx4 v[6:7], off
	v_add_u32_e32 v24, s2, v141
	s_waitcnt vmcnt(8)
	s_barrier
	ds_read_b128 v[2:5], v24
	v_or_b32_e32 v39, 2, v144
	v_bitop3_b32 v6, v23, v39, 7 bitop3:0x6c
	v_lshl_or_b32 v145, v6, 4, v22
	v_add_u32_e32 v42, s2, v145
	ds_read_b128 v[18:21], v42
	s_waitcnt vmcnt(8) lgkmcnt(0)
	v_mfma_f32_32x32x16_bf16 v[2:17], v[2:5], v[98:101], 0
	v_or_b32_e32 v40, 4, v144
	v_bitop3_b32 v25, v23, v40, 7 bitop3:0x6c
	v_lshl_or_b32 v147, v25, 4, v22
	v_add_u32_e32 v46, s2, v147
	v_or_b32_e32 v41, 6, v144
	v_bitop3_b32 v23, v23, v41, 7 bitop3:0x6c
	v_lshl_or_b32 v148, v23, 4, v22
	v_mfma_f32_32x32x16_bf16 v[2:17], v[18:21], v[102:105], v[2:17]
	ds_read_b128 v[18:21], v46
	v_add_u32_e32 v47, s2, v148
	ds_read_b128 v[42:45], v42 offset:4096
	s_cmp_lt_i32 s15, 4
	s_waitcnt lgkmcnt(1)
	v_mfma_f32_32x32x16_bf16 v[2:17], v[18:21], v[106:109], v[2:17]
	ds_read_b128 v[18:21], v47
	s_waitcnt lgkmcnt(0)
	v_mfma_f32_32x32x16_bf16 v[2:17], v[18:21], v[110:113], v[2:17]
	ds_read_b128 v[18:21], v24 offset:4096
	s_waitcnt lgkmcnt(0)
	v_mfma_f32_32x32x16_bf16 v[18:33], v[18:21], v[98:101], 0
	v_mfma_f32_32x32x16_bf16 v[18:33], v[42:45], v[102:105], v[18:33]
	ds_read_b128 v[42:45], v46 offset:4096
	s_waitcnt lgkmcnt(0)
	v_mfma_f32_32x32x16_bf16 v[18:33], v[42:45], v[106:109], v[18:33]
	ds_read_b128 v[42:45], v47 offset:4096
	s_waitcnt lgkmcnt(0)
	v_mfma_f32_32x32x16_bf16 v[18:33], v[42:45], v[110:113], v[18:33]
	s_nop 1
	v_max_f32_e32 v42, v3, v3
	v_max_f32_e32 v43, v2, v2
	v_max_f32_e32 v42, v43, v42
	v_max3_f32 v42, v42, v4, v5
	v_max3_f32 v42, v42, v6, v7
	v_max3_f32 v42, v42, v8, v9
	v_max3_f32 v42, v42, v10, v11
	v_max3_f32 v42, v42, v12, v13
	v_max3_f32 v42, v42, v14, v15
	v_max3_f32 v42, v42, v16, v17
	v_max3_f32 v42, v42, v18, v19
	v_max3_f32 v42, v42, v20, v21
	v_max3_f32 v42, v42, v22, v23
	v_max3_f32 v42, v42, v24, v25
	v_max3_f32 v42, v42, v26, v27
	v_max3_f32 v42, v42, v28, v29
	v_max3_f32 v42, v42, v30, v31
	v_max3_f32 v42, v42, v32, v33
	v_mul_f32_e32 v42, 1.0, v42
	v_mov_b32_e32 v43, v42
	s_nop 1
	v_permlane32_swap_b32_e32 v42, v43
	s_cbranch_scc1 .LBB0_470
	s_nop 0
; #define VLOAD(dst, sbv, q) do { _Pragma("unroll") for (int d_ = 0; d_ < 4; ++d_) dst[d_] = *(const lds_bf16x8*)((sbv) + vo[q] + d_ * 4096); } while (0)
; DI void diff_unit(KP p, int l, int b, int h, int qb, int isctx, float lamv, float lam_init, char* ldsc) {
;     ...
; #pragma unroll
;   for (int d = 0; d < 4; ++d)
; #pragma unroll
;     for (int i = 0; i < 16; ++i) o[d][i] = 0.f;
;   float m, lsum;
;   const bf16_t* vt = p->Vtd + (size_t)((b * 4 + h) * 128) * NKEY;
;   const bf16_t* Pk = p->P + 1024 + h * 128;
;   const int row8 = 8 * w + (lane >> 3), swz = ((lane & 7) ^ ((row8 >> 1) & 7)) << 4;
;   const unsigned kq = (unsigned)(row8 * (INC * 2) + swz), vq = (unsigned)(row8 * (NKEY * 2) + swz);
;     ...
;   asm volatile("s_waitcnt vmcnt(0)" ::: "memory");
;   __syncthreads();
;   DISSUE(0, 0);
;   DISSUE(1, 1);
;   asm volatile("s_waitcnt vmcnt(4)" ::: "memory");
;   __builtin_amdgcn_s_barrier();
;   bf16x8 P[4];
;   {
;     f32x16 st[2];
;     qk_tile(qf, L + comp * 8192, ko, st);
;     m = tile_max(st);
;     lsum = exp_pack(st, m, P);
;   }
;   int stg = 0;
;   bool need = false; float alpha = 1.f;
;   if (w >= 4) __builtin_amdgcn_s_setprio(1);
;   bf16x8 vA[4], vB[4];
;   VLOAD(vA, L + 16384, 0); VLOAD(vB, L + 16384, 1);
.LBB0_470:
	v_and_b32_e32 v133, 63, v38
	v_max_f32_e32 v38, v43, v43
	v_max_f32_e32 v42, v42, v42
	v_max_f32_e32 v153, v42, v38
	v_sub_f32_e32 v252, 0, v153
	v_mov_b32_e32 v253, v252
	v_fma_f32 v2, v2, 1.0, -v153
	v_fma_f32 v3, v3, 1.0, -v153
	v_exp_f32_e32 v2, v2
	v_exp_f32_e32 v3, v3
	v_fma_f32 v10, v10, 1.0, -v153
	v_exp_f32_e32 v10, v10
	v_fma_f32 v11, v11, 1.0, -v153
	v_fma_f32 v4, v4, 1.0, -v153
	v_exp_f32_e32 v11, v11
	v_fma_f32 v12, v12, 1.0, -v153
	v_exp_f32_e32 v4, v4
	v_fma_f32 v5, v5, 1.0, -v153
	v_exp_f32_e32 v12, v12
	v_fma_f32 v13, v13, 1.0, -v153
	v_exp_f32_e32 v5, v5
	v_fma_f32 v6, v6, 1.0, -v153
	v_cvt_pk_bf16_f32 v66, v2, v3
	v_exp_f32_e32 v13, v13
	v_fma_f32 v14, v14, 1.0, -v153
	v_add_f32_e32 v2, 0, v2
	v_exp_f32_e32 v6, v6
	v_fma_f32 v7, v7, 1.0, -v153
	v_exp_f32_e32 v14, v14
	v_fma_f32 v15, v15, 1.0, -v153
	v_add_f32_e32 v2, v3, v2
	v_add_f32_e32 v3, 0, v10
	v_exp_f32_e32 v7, v7
	v_fma_f32 v8, v8, 1.0, -v153
	v_exp_f32_e32 v15, v15
	v_fma_f32 v16, v16, 1.0, -v153
	v_add_f32_e32 v3, v11, v3
	v_exp_f32_e32 v8, v8
	v_fma_f32 v9, v9, 1.0, -v153
	v_exp_f32_e32 v16, v16
	v_fma_f32 v17, v17, 1.0, -v153
	v_add_f32_e32 v2, v4, v2
	v_add_f32_e32 v3, v12, v3
	v_exp_f32_e32 v9, v9
	v_exp_f32_e32 v17, v17
	v_fma_f32 v18, v18, 1.0, -v153
	v_fma_f32 v26, v26, 1.0, -v153
	v_add_f32_e32 v2, v5, v2
	v_add_f32_e32 v3, v13, v3
	v_exp_f32_e32 v18, v18
	v_fma_f32 v19, v19, 1.0, -v153
	v_exp_f32_e32 v26, v26
	v_fma_f32 v27, v27, 1.0, -v153
	v_add_f32_e32 v2, v6, v2
	v_add_f32_e32 v3, v14, v3
	v_exp_f32_e32 v19, v19
	v_fma_f32 v20, v20, 1.0, -v153
	v_exp_f32_e32 v27, v27
	v_fma_f32 v28, v28, 1.0, -v153
	v_add_f32_e32 v2, v7, v2
	v_add_f32_e32 v3, v15, v3
	v_exp_f32_e32 v20, v20
	v_fma_f32 v21, v21, 1.0, -v153
	v_exp_f32_e32 v28, v28
	v_fma_f32 v29, v29, 1.0, -v153
	v_add_f32_e32 v2, v8, v2
	v_add_f32_e32 v3, v16, v3
	v_exp_f32_e32 v21, v21
	v_fma_f32 v22, v22, 1.0, -v153
	v_exp_f32_e32 v29, v29
	v_fma_f32 v30, v30, 1.0, -v153
	v_add_f32_e32 v2, v9, v2
	v_add_f32_e32 v3, v17, v3
	v_cvt_pk_bf16_f32 v67, v4, v5
	v_exp_f32_e32 v22, v22
	v_fma_f32 v23, v23, 1.0, -v153
	v_exp_f32_e32 v30, v30
	v_fma_f32 v31, v31, 1.0, -v153
	v_add_f32_e32 v2, v2, v3
	v_add_f32_e32 v3, 0, v18
	v_add_f32_e32 v4, 0, v26
	v_exp_f32_e32 v23, v23
	v_fma_f32 v24, v24, 1.0, -v153
	v_exp_f32_e32 v31, v31
	v_fma_f32 v32, v32, 1.0, -v153
	v_add_f32_e32 v3, v19, v3
	v_add_f32_e32 v4, v27, v4
	v_exp_f32_e32 v24, v24
	v_fma_f32 v25, v25, 1.0, -v153
	v_exp_f32_e32 v32, v32
	v_fma_f32 v33, v33, 1.0, -v153
	v_add_f32_e32 v3, v20, v3
	v_add_f32_e32 v4, v28, v4
	v_exp_f32_e32 v25, v25
	v_exp_f32_e32 v33, v33
	v_add_f32_e32 v3, v21, v3
	v_add_f32_e32 v4, v29, v4
	v_add_f32_e32 v3, v22, v3
	v_add_f32_e32 v4, v30, v4
	v_add_f32_e32 v3, v23, v3
	v_add_f32_e32 v4, v31, v4
	v_add_f32_e32 v3, v24, v3
	v_add_f32_e32 v4, v32, v4
	v_lshlrev_b32_e32 v35, 7, v35
	v_bitop3_b32 v38, v144, v34, 7 bitop3:0x78
	v_add_f32_e32 v3, v25, v3
	v_add_f32_e32 v4, v33, v4
	v_lshl_or_b32 v150, v38, 4, v35
	v_bitop3_b32 v38, v39, v34, 7 bitop3:0x78
	v_add_f32_e32 v3, v3, v4
	v_lshl_or_b32 v151, v38, 4, v35
	v_add_f32_e32 v152, v2, v3
	v_add_u32_e32 v2, 0, v150
	ds_read_b128 v[86:89], v2 offset:16384
	ds_read_b128 v[82:85], v2 offset:20480
	ds_read_b128 v[78:81], v2 offset:24576
	ds_read_b128 v[74:77], v2 offset:28672
	v_add_u32_e32 v2, 0, v151
	s_add_i32 s2, s18, s17
	s_mul_i32 s15, s15, 0x21000
	ds_read_b128 v[126:129], v2 offset:16384
	ds_read_b128 v[122:125], v2 offset:20480
	ds_read_b128 v[94:97], v2 offset:24576
	ds_read_b128 v[90:93], v2 offset:28672
	v_lshl_add_u64 v[136:137], s[10:11], 0, v[0:1]
	s_add_i32 s10, s16, 0xffffff80
	s_mul_hi_i32 s11, s2, 0x4200
	s_mulk_i32 s2, 0x4200
	v_mov_b32_e32 v0, s15
	v_mad_u32_u24 v0, v36, s65, v0
	s_add_u32 s4, s4, s2
	v_or_b32_e32 v0, v0, v37
	s_addc_u32 s5, s5, s11
	v_cvt_pk_bf16_f32 v72, v14, v15
	v_bitop3_b32 v38, v40, v34, 7 bitop3:0x78
	v_bitop3_b32 v34, v41, v34, 7 bitop3:0x78
	v_lshl_add_u64 v[2:3], s[4:5], 0, v[0:1]
	s_mov_b64 s[4:5], 0x108180
	v_mov_b32_e32 v14, v1
	v_mov_b32_e32 v15, v1
	v_cvt_pk_bf16_f32 v68, v6, v7
	v_cvt_pk_bf16_f32 v69, v8, v9
	v_cvt_pk_bf16_f32 v70, v10, v11
	v_cvt_pk_bf16_f32 v71, v12, v13
	v_cvt_pk_bf16_f32 v118, v18, v19
	v_cvt_pk_bf16_f32 v119, v20, v21
	v_cvt_pk_bf16_f32 v120, v22, v23
	v_cvt_pk_bf16_f32 v121, v24, v25
	v_cvt_pk_bf16_f32 v114, v26, v27
	v_cvt_pk_bf16_f32 v115, v28, v29
	v_cvt_pk_bf16_f32 v116, v30, v31
	v_cvt_pk_bf16_f32 v117, v32, v33
	v_lshl_or_b32 v149, v38, 4, v35
	v_lshl_or_b32 v146, v34, 4, v35
	v_lshl_add_u64 v[138:139], v[2:3], 0, s[4:5]
	v_mov_b32_e32 v0, v1
	v_mov_b32_e32 v2, v1
	v_mov_b32_e32 v3, v1
	v_mov_b32_e32 v4, v1
	v_mov_b32_e32 v5, v1
	v_mov_b32_e32 v6, v1
	v_mov_b32_e32 v7, v1
	v_mov_b32_e32 v8, v1
	v_mov_b32_e32 v9, v1
	v_mov_b32_e32 v10, v1
	v_mov_b32_e32 v11, v1
	v_mov_b32_e32 v12, v1
	v_mov_b32_e32 v13, v1
	v_mov_b64_e32 v[64:65], v[14:15]
	v_mov_b64_e32 v[48:49], v[14:15]
	v_mov_b64_e32 v[32:33], v[14:15]
	v_cvt_pk_bf16_f32 v73, v16, v17
	v_mov_b64_e32 v[62:63], v[12:13]
	v_mov_b64_e32 v[60:61], v[10:11]
	v_mov_b64_e32 v[58:59], v[8:9]
	v_mov_b64_e32 v[56:57], v[6:7]
	v_mov_b64_e32 v[54:55], v[4:5]
	v_mov_b64_e32 v[52:53], v[2:3]
	v_mov_b64_e32 v[50:51], v[0:1]
	v_mov_b64_e32 v[46:47], v[12:13]
	v_mov_b64_e32 v[44:45], v[10:11]
	v_mov_b64_e32 v[42:43], v[8:9]
	v_mov_b64_e32 v[40:41], v[6:7]
	v_mov_b64_e32 v[38:39], v[4:5]
	v_mov_b64_e32 v[36:37], v[2:3]
	v_mov_b64_e32 v[34:35], v[0:1]
	v_mov_b64_e32 v[30:31], v[12:13]
	v_mov_b64_e32 v[28:29], v[10:11]
	v_mov_b64_e32 v[26:27], v[8:9]
	v_mov_b64_e32 v[24:25], v[6:7]
	v_mov_b64_e32 v[22:23], v[4:5]
	v_mov_b64_e32 v[20:21], v[2:3]
	v_mov_b64_e32 v[18:19], v[0:1]
	v_mov_b64_e32 v[16:17], v[14:15]
	v_ashrrev_i32_e32 v135, 31, v134
	v_mov_b32_e32 v140, 1.0
	s_mov_b64 s[4:5], 0
	s_mov_b32 s17, 0
	v_mov_b64_e32 v[14:15], v[12:13]
	v_mov_b64_e32 v[12:13], v[10:11]
	v_mov_b64_e32 v[10:11], v[8:9]
	v_mov_b64_e32 v[8:9], v[6:7]
	v_mov_b64_e32 v[6:7], v[4:5]
	v_mov_b64_e32 v[4:5], v[2:3]
	v_mov_b64_e32 v[2:3], v[0:1]
	s_mov_b32 s11, 0

; #define MFMA32(a, b, c) __builtin_amdgcn_mfma_f32_32x32x16_bf16((a), (b), (c), 0, 0, 0)
; #define VLOAD(dst, sbv, q) do { _Pragma("unroll") for (int d_ = 0; d_ < 4; ++d_) dst[d_] = *(const lds_bf16x8*)((sbv) + vo[q] + d_ * 4096); } while (0)
; #define FENCE __builtin_amdgcn_sched_barrier(0)
; DI void diff_unit(KP p, int l, int b, int h, int qb, int isctx, float lamv, float lam_init, char* ldsc) {
;     ...
;     const lds_u8* sbv = L + stg * STG + 16384;
;     const lds_u8* sbk = L + stg1 * STG + comp * 8192;
;     bf16x8 kf[2][4];
;     f32x16 st[2];
; #pragma unroll
;     for (int t = 0; t < 2; ++t)
; #pragma unroll
;       for (int ks = 0; ks < 4; ++ks) kf[t][ks] = *(const lds_bf16x8*)(sbk + ko[ks] + t * 4096);
;     FENCE;
;     pv_grp(o, vA, P[0]); pv_grp(o, vB, P[1]);
;     VLOAD(vA, sbv, 2); VLOAD(vB, sbv, 3);
;     FENCE;
; #pragma unroll
;     for (int i = 0; i < 16; ++i) { st[0][i] = 0.f; st[1][i] = 0.f; }
; #pragma unroll
;     for (int ks = 0; ks < 4; ++ks) st[0] = MFMA32(kf[0][ks], qf[ks], st[0]);
; #pragma unroll
;     for (int ks = 0; ks < 4; ++ks) st[1] = MFMA32(kf[1][ks], qf[ks], st[1]);
;     FENCE;
;     pv_grp(o, vA, P[2]);
;     const float mx = tile_max(st);
;     need = !__all(mx <= m + 8.0f);
;     const float mn = need ? fmaxf(m, mx) : m;
;     alpha = __builtin_amdgcn_exp2f(m - mn);
;     FENCE;
.LBB0_477:
	s_add_i32 s2, s17, 1
	s_and_b32 s16, s2, 3
	s_lshl_b32 s2, s16, 15
	s_add_i32 s15, s2, 0
	s_add_i32 s2, s15, s14
	v_add_u32_e32 v0, s2, v141
	v_add_u32_e32 v140, s2, v145
	v_add_u32_e32 v191, s2, v147
	v_add_u32_e32 v216, s2, v148
	ds_read_b128 v[154:157], v0
	ds_read_b128 v[192:195], v0 offset:4096
	ds_read_b128 v[196:199], v140
	ds_read_b128 v[200:203], v140 offset:4096
	ds_read_b128 v[204:207], v191
	ds_read_b128 v[208:211], v191 offset:4096
	ds_read_b128 v[212:215], v216
	ds_read_b128 v[216:219], v216 offset:4096
	s_lshl_b32 s2, s17, 15
	s_add_i32 s2, s2, 0
	s_waitcnt lgkmcnt(8)
	v_mfma_f32_32x32x16_bf16 v[50:65], v[86:89], v[66:69], v[50:65]
	v_add_u32_e32 v0, s2, v149
	ds_read_b128 v[220:223], v0 offset:24576
	ds_read_b128 v[224:227], v0 offset:28672
	s_add_i32 s18, s3, 0xc0
	s_add_i32 s19, s10, 64
	s_cmp_eq_u32 s11, 0
	s_cselect_b32 s19, s18, s19
	s_add_i32 s18, s17, 3
	s_and_b32 s18, s18, 3
	s_lshl_b32 s18, s18, 15
	s_add_i32 s18, s13, s18
	v_mad_i64_i32 v[244:245], vcc, s19, v185, v[136:137]
	v_lshl_add_u64 v[246:247], v[244:245], 0, s[96:97]
	v_lshl_add_u64 v[244:245], v[244:245], 0, s[52:53]
	v_lshl_add_u64 v[248:249], v[138:139], 0, s[60:61]
	s_mov_b32 m0, s18
	v_mfma_f32_32x32x16_bf16 v[34:49], v[82:85], v[66:69], v[34:49]
	global_load_lds_dwordx4 v[246:247], off
	s_add_i32 m0, s18, 0x2000
	v_mfma_f32_32x32x16_bf16 v[18:33], v[78:81], v[66:69], v[18:33]
	v_mfma_f32_32x32x16_bf16 v[2:17], v[74:77], v[66:69], v[2:17]
	v_mov_b64_e32 v[66:67], v[252:253]
	v_mov_b64_e32 v[68:69], v[252:253]
	v_mov_b64_e32 v[74:75], v[252:253]
	global_load_lds_dwordx4 v[244:245], off
	s_add_i32 m0, s18, 0x4000
	v_mfma_f32_32x32x16_bf16 v[50:65], v[126:129], v[70:73], v[50:65]
	v_mov_b64_e32 v[76:77], v[252:253]
	v_mov_b64_e32 v[78:79], v[252:253]
	v_mov_b64_e32 v[80:81], v[252:253]
	ds_read_b128 v[126:129], v0 offset:20480
	v_mfma_f32_32x32x16_bf16 v[34:49], v[122:125], v[70:73], v[34:49]
	v_mov_b64_e32 v[82:83], v[252:253]
	v_mov_b64_e32 v[84:85], v[252:253]
	ds_read_b128 v[122:125], v0 offset:16384
	v_add_u32_e32 v0, s2, v146
	ds_read_b128 v[228:231], v0 offset:16384
	ds_read_b128 v[232:235], v0 offset:20480
	ds_read_b128 v[236:239], v0 offset:24576
	ds_read_b128 v[240:243], v0 offset:28672
	v_mfma_f32_32x32x16_bf16 v[18:33], v[94:97], v[70:73], v[18:33]
	v_mov_b64_e32 v[86:87], v[252:253]
	v_mov_b64_e32 v[88:89], v[252:253]
	v_mov_b64_e32 v[94:95], v[252:253]
	v_mov_b64_e32 v[96:97], v[252:253]
	v_mfma_f32_32x32x16_bf16 v[2:17], v[90:93], v[70:73], v[2:17]
	v_mov_b64_e32 v[70:71], v[252:253]
	v_mov_b64_e32 v[72:73], v[252:253]
	v_mov_b64_e32 v[90:91], v[252:253]
	v_mov_b64_e32 v[92:93], v[252:253]
	global_load_lds_dwordx4 v[248:249], off
	s_add_i32 m0, s18, 0x6000
	s_waitcnt lgkmcnt(8)
	v_mfma_f32_32x32x16_bf16 v[66:81], v[192:195], v[98:101], v[66:81]
	v_mfma_f32_32x32x16_bf16 v[82:97], v[154:157], v[98:101], v[82:97]
	v_mfma_f32_32x32x16_bf16 v[66:81], v[200:203], v[102:105], v[66:81]
	v_mfma_f32_32x32x16_bf16 v[82:97], v[196:199], v[102:105], v[82:97]
	global_load_lds_dwordx4 v[138:139], off
	v_mfma_f32_32x32x16_bf16 v[66:81], v[208:211], v[106:109], v[66:81]
	v_mfma_f32_32x32x16_bf16 v[82:97], v[204:207], v[106:109], v[82:97]
	v_mfma_f32_32x32x16_bf16 v[66:81], v[216:219], v[110:113], v[66:81]
	v_mfma_f32_32x32x16_bf16 v[82:97], v[212:215], v[110:113], v[82:97]
	s_waitcnt lgkmcnt(0)
	v_mfma_f32_32x32x16_bf16 v[50:65], v[122:125], v[118:121], v[50:65]
	s_nop 9
	v_max3_f32 v0, v82, v83, v84
	v_max3_f32 v250, v66, v67, v68
	v_mfma_f32_32x32x16_bf16 v[34:49], v[126:129], v[118:121], v[34:49]
	v_max3_f32 v0, v0, v85, v86
	v_max3_f32 v250, v250, v69, v70
	v_max3_f32 v0, v0, v87, v88
	v_max3_f32 v250, v250, v71, v72
	v_max3_f32 v0, v0, v89, v90
	v_mfma_f32_32x32x16_bf16 v[18:33], v[220:223], v[118:121], v[18:33]
	v_max3_f32 v250, v250, v73, v74
	v_max3_f32 v0, v0, v91, v92
	v_max3_f32 v250, v250, v75, v76
	v_max3_f32 v0, v0, v93, v94
	v_max3_f32 v250, v250, v77, v78
	v_mfma_f32_32x32x16_bf16 v[2:17], v[224:227], v[118:121], v[2:17]
	v_max3_f32 v0, v0, v95, v96
	v_max3_f32 v250, v250, v79, v80
	v_max_f32_e32 v0, v0, v97
	v_max_f32_e32 v250, v250, v81
	v_max_f32_e32 v0, v0, v250
	v_mov_b32_e32 v118, v0
	s_nop 1
	v_permlane32_swap_b32_e32 v0, v118
	v_max_f32_e32 v0, v0, v118
	v_cmp_ge_f32_e32 vcc, 0x41000000, v0
	s_cmp_lg_u64 vcc, exec
	s_cselect_b64 s[4:5], -1, 0
	v_max_f32_e32 v0, 0, v0
	v_cndmask_b32_e64 v0, 0, v0, s[4:5]
	v_sub_f32_e32 v252, v252, v0
	v_exp_f32_e64 v140, -v0
	v_mov_b32_e32 v253, v252
	s_andn2_b64 vcc, exec, s[4:5]
	s_cbranch_vccnz .Ldiff_nosub
	v_sub_f32_e32 v82, v82, v0
	v_sub_f32_e32 v83, v83, v0
	v_sub_f32_e32 v84, v84, v0
	v_sub_f32_e32 v85, v85, v0
	v_sub_f32_e32 v86, v86, v0
	v_sub_f32_e32 v87, v87, v0
	v_sub_f32_e32 v88, v88, v0
	v_sub_f32_e32 v89, v89, v0
	v_sub_f32_e32 v90, v90, v0
	v_sub_f32_e32 v91, v91, v0
	v_sub_f32_e32 v92, v92, v0
	v_sub_f32_e32 v93, v93, v0
	v_sub_f32_e32 v94, v94, v0
	v_sub_f32_e32 v95, v95, v0
	v_sub_f32_e32 v96, v96, v0
	v_sub_f32_e32 v97, v97, v0
	v_sub_f32_e32 v66, v66, v0
	v_sub_f32_e32 v67, v67, v0
	v_sub_f32_e32 v68, v68, v0
	v_sub_f32_e32 v69, v69, v0
	v_sub_f32_e32 v70, v70, v0
	v_sub_f32_e32 v71, v71, v0
	v_sub_f32_e32 v72, v72, v0
	v_sub_f32_e32 v73, v73, v0
	v_sub_f32_e32 v74, v74, v0
	v_sub_f32_e32 v75, v75, v0
	v_sub_f32_e32 v76, v76, v0
	v_sub_f32_e32 v77, v77, v0
	v_sub_f32_e32 v78, v78, v0
	v_sub_f32_e32 v79, v79, v0
	v_sub_f32_e32 v80, v80, v0
	v_sub_f32_e32 v81, v81, v0
; #define VLOAD(dst, sbv, q) do { _Pragma("unroll") for (int d_ = 0; d_ < 4; ++d_) dst[d_] = *(const lds_bf16x8*)((sbv) + vo[q] + d_ * 4096); } while (0)
; #define FENCE __builtin_amdgcn_sched_barrier(0)
; DI void diff_unit(KP p, int l, int b, int h, int qb, int isctx, float lamv, float lam_init, char* ldsc) {
;     ...
;     float ps = exp_pack1<0>(st, mn, P[0]);
;     ps += exp_pack1<1>(st, mn, P[1]);
;     ps += exp_pack1<2>(st, mn, P[2]);
;     pv_grp(o, vB, P[3]);
;     ps += exp_pack1<3>(st, mn, P[3]);
; #pragma unroll
;     for (int q = 0; q < 4; ++q) { __builtin_amdgcn_sched_group_barrier(0x402, 18, 0); __builtin_amdgcn_sched_group_barrier(0x008, 1, 0); }
;     lsum = lsum * alpha + ps; m = mn;
;     FENCE;
;     { const lds_u8* sbn = L + stg1 * STG + 16384; VLOAD(vA, sbn, 0); VLOAD(vB, sbn, 1); }
;     stg = stg1;
.Ldiff_nosub:
	v_exp_f32_e32 v122, v82
	v_exp_f32_e32 v124, v83
	v_exp_f32_e32 v126, v84
	v_exp_f32_e32 v128, v85
	v_exp_f32_e32 v156, v86
	v_exp_f32_e32 v192, v87
	v_exp_f32_e32 v194, v88
	v_exp_f32_e32 v196, v89
	v_exp_f32_e32 v123, v90
	v_mfma_f32_32x32x16_bf16 v[50:65], v[228:231], v[114:117], v[50:65]
	v_exp_f32_e32 v125, v91
	v_exp_f32_e32 v127, v92
	v_exp_f32_e32 v129, v93
	v_exp_f32_e32 v157, v94
	v_exp_f32_e32 v193, v95
	v_exp_f32_e32 v195, v96
	v_exp_f32_e32 v197, v97
	v_exp_f32_e32 v83, v66
	v_exp_f32_e32 v67, v67
	v_mfma_f32_32x32x16_bf16 v[34:49], v[232:235], v[114:117], v[34:49]
	v_exp_f32_e32 v85, v68
	v_exp_f32_e32 v69, v69
	v_exp_f32_e32 v87, v70
	v_exp_f32_e32 v71, v71
	v_exp_f32_e32 v89, v72
	v_exp_f32_e32 v73, v73
	v_exp_f32_e32 v82, v74
	v_exp_f32_e32 v66, v75
	v_exp_f32_e32 v84, v76
	v_mfma_f32_32x32x16_bf16 v[18:33], v[236:239], v[114:117], v[18:33]
	v_exp_f32_e32 v68, v77
	v_exp_f32_e32 v86, v78
	v_exp_f32_e32 v70, v79
	v_exp_f32_e32 v88, v80
	v_exp_f32_e32 v72, v81
	v_mfma_f32_32x32x16_bf16 v[2:17], v[240:243], v[114:117], v[2:17]
	v_cvt_pk_bf16_f32 v118, v83, v67
	v_cvt_pk_bf16_f32 v114, v82, v66
	v_add_f32_e64 v66, v66, v82
	v_add_f32_e64 v67, v67, v83
	v_cvt_pk_bf16_f32 v119, v85, v69
	v_pk_add_f32 v[66:67], v[84:85], v[66:67]
	v_cvt_pk_bf16_f32 v120, v87, v71
	v_pk_add_f32 v[66:67], v[68:69], v[66:67]
	v_cvt_pk_bf16_f32 v121, v89, v73
	v_pk_add_f32 v[66:67], v[86:87], v[66:67]
	v_cvt_pk_bf16_f32 v115, v84, v68
	v_pk_add_f32 v[66:67], v[70:71], v[66:67]
	v_cvt_pk_bf16_f32 v116, v86, v70
	v_pk_add_f32 v[66:67], v[88:89], v[66:67]
	v_cvt_pk_bf16_f32 v117, v88, v72
	v_pk_add_f32 v[90:91], v[72:73], v[66:67]
	v_add_u32_e32 v0, s15, v150
	v_pk_add_f32 v[92:93], v[124:125], v[122:123]
	ds_read_b128 v[86:89], v0 offset:16384
	ds_read_b128 v[82:85], v0 offset:20480
	v_pk_add_f32 v[92:93], v[126:127], v[92:93]
	ds_read_b128 v[78:81], v0 offset:24576
	ds_read_b128 v[74:77], v0 offset:28672
	v_pk_add_f32 v[92:93], v[128:129], v[92:93]
	v_cvt_pk_bf16_f32 v66, v122, v124
	v_pk_add_f32 v[92:93], v[156:157], v[92:93]
	v_cvt_pk_bf16_f32 v67, v126, v128
	v_pk_add_f32 v[92:93], v[192:193], v[92:93]
	v_cvt_pk_bf16_f32 v70, v123, v125
	v_pk_add_f32 v[92:93], v[194:195], v[92:93]
	v_cvt_pk_bf16_f32 v71, v127, v129
	v_pk_add_f32 v[92:93], v[196:197], v[92:93]
	s_add_i32 s11, s11, 1
	v_add_f32_e32 v0, v92, v93
	v_add_f32_e32 v0, v91, v0
	v_add_f32_e32 v0, v90, v0
	v_add_u32_e32 v90, s15, v151
	ds_read_b128 v[126:129], v90 offset:16384
	ds_read_b128 v[122:125], v90 offset:20480
	ds_read_b128 v[94:97], v90 offset:24576
	ds_read_b128 v[90:93], v90 offset:28672
	s_add_i32 s10, s10, 64
	v_cvt_pk_bf16_f32 v68, v156, v192
	v_cvt_pk_bf16_f32 v69, v194, v196
	v_cvt_pk_bf16_f32 v72, v157, v193
	v_cvt_pk_bf16_f32 v73, v195, v197
	v_fma_f32 v152, v152, v140, v0
	s_cmpk_eq_i32 s11, 0x83
	v_lshl_add_u64 v[138:139], v[138:139], 0, s[46:47]
	s_cbranch_scc1 .LBB0_479
	s_mov_b32 s17, s16
	s_branch .LBB0_471
